# v031 + next-tile coordinate computation: division by the (always 8) group size replaced by shift/mask, removing ~30 scalar/vector instructions and a v_rcp/readfirstlane round trip per tile per wave
# baseline (speedup 1.0000x reference)
;     DI bool next(int i, Unit& u) const { if (i > 0 || c >= 64) return false; u.pm = c & 31; u.pn = 0; u.src = c >> 5; return true; }
;     DI bool next(int i, Unit& u) const {
;         const int it = CHAIN ? (i >> 1) : i; u.src = CHAIN ? (i & 1) : 0;
;         const long L = (long)it * G + c; if (L >= nwg) return false;
;         int wgid = (int)L; { const int q = nwg / NXCD, r = nwg % NXCD, xcd = wgid % NXCD, off = wgid / NXCD; wgid = (xcd < r ? xcd * (q + 1) : r * (q + 1) + (xcd - r) * q) + off; }
;         const int nig = WGM * nN, gid = wgid / nig, fm = gid * WGM, gsz = (nM - fm) < WGM ? (nM - fm) : WGM;
;         u.pm = fm + ((wgid % nig) % gsz); u.pn = (wgid % nig) / gsz; return true;
.LBB0_176:
	s_add_i32 s53, s53, 1
	s_mul_i32 s4, s53, s56
	s_mul_hi_u32 s5, s53, s3
	s_add_i32 s5, s5, s4
	s_mul_i32 s4, s53, s3
	s_add_u32 s36, s4, s2
	s_addc_u32 s37, s5, s47
	v_cmp_gt_i64_e32 vcc, s[36:37], v[144:145]
	v_cmp_lt_i64_e64 s[4:5], s[36:37], v[142:143]
	s_cbranch_vccnz .LBB0_178
	s_ashr_i32 s20, s36, 31
	s_lshr_b32 s20, s20, 29
	s_add_i32 s20, s36, s20
	s_ashr_i32 s21, s20, 3
	s_and_b32 s20, s20, -8
	s_sub_i32 s20, s36, s20
	s_cmp_lt_i32 s20, 0
	s_cselect_b32 s34, s48, 0x2c0
	s_mul_i32 s20, s20, s34
	s_add_i32 s20, s20, s21
	s_mul_hi_i32 s21, s20, 0x2e8ba2e9
	s_lshr_b32 s34, s21, 31
	s_ashr_i32 s21, s21, 5
	s_add_i32 s21, s21, s34
	s_lshl_b32 s34, s21, 3
	s_sub_i32 s35, 0x100, s34
	s_min_i32 s35, s35, 8
	s_mulk_i32 s21, 0xb0
	s_sub_i32 s21, s20, s21
	s_lshr_b32 s20, s21, 3
	s_and_b32 s21, s21, 7
	s_add_i32 s34, s34, s21

;     DI bool next(int i, Unit& u) const {
;     ...
;         int wgid = (int)L; { const int q = nwg / NXCD, r = nwg % NXCD, xcd = wgid % NXCD, off = wgid / NXCD; wgid = (xcd < r ? xcd * (q + 1) : r * (q + 1) + (xcd - r) * q) + off; }
;         const int nig = WGM * nN, gid = wgid / nig, fm = gid * WGM, gsz = (nM - fm) < WGM ? (nM - fm) : WGM;
;         u.pm = fm + ((wgid % nig) % gsz); u.pn = (wgid % nig) / gsz; return true;
.LBB0_272:
	s_ashr_i32 s6, s34, 3
	s_add_i32 s6, s40, s6
	s_ashr_i32 s7, s6, 31
	s_lshr_b32 s7, s7, 27
	s_add_i32 s7, s6, s7
	s_ashr_i32 s34, s7, 5
	s_lshl_b32 s34, s34, 3
	s_sub_i32 s35, 0x100, s34
	s_min_i32 s35, s35, 8
	s_andn2_b32 s7, s7, 31
	s_sub_i32 s6, s6, s7
	s_lshr_b32 s56, s6, 3
	s_and_b32 s6, s6, 7
	s_add_i32 s57, s34, s6

;     DI bool next(int i, Unit& u) const { if (i > 0 || c >= 64) return false; u.pm = c & 31; u.pn = 0; u.src = c >> 5; return true; }
;     DI bool next(int i, Unit& u) const {
;         const int it = CHAIN ? (i >> 1) : i; u.src = CHAIN ? (i & 1) : 0;
;         const long L = (long)it * G + c; if (L >= nwg) return false;
;         int wgid = (int)L; { const int q = nwg / NXCD, r = nwg % NXCD, xcd = wgid % NXCD, off = wgid / NXCD; wgid = (xcd < r ? xcd * (q + 1) : r * (q + 1) + (xcd - r) * q) + off; }
;         const int nig = WGM * nN, gid = wgid / nig, fm = gid * WGM, gsz = (nM - fm) < WGM ? (nM - fm) : WGM;
;         u.pm = fm + ((wgid % nig) % gsz); u.pn = (wgid % nig) / gsz; return true;
.LBB0_378:
	s_add_i32 s97, s97, 1
	s_mul_i32 s8, s97, s91
	s_mul_hi_u32 s9, s97, s3
	s_add_i32 s9, s9, s8
	s_mul_i32 s8, s97, s3
	s_add_u32 s60, s8, s2
	s_addc_u32 s61, s9, s92
	v_cmp_gt_i64_e32 vcc, s[60:61], v[168:169]
	v_cmp_lt_i64_e64 s[8:9], s[60:61], v[166:167]
	s_cbranch_vccnz .LBB0_380
	s_ashr_i32 s11, s60, 31
	s_lshr_b32 s11, s11, 29
	s_add_i32 s11, s60, s11
	s_ashr_i32 s13, s11, 3
	s_and_b32 s11, s11, -8
	s_sub_i32 s11, s60, s11
	s_cmp_lt_i32 s11, 0
	s_cselect_b32 s28, s93, 0x280
	s_mul_i32 s11, s11, s28
	s_add_i32 s11, s11, s13
	s_mul_hi_i32 s13, s11, 0x66666667
	s_lshr_b32 s28, s13, 31
	s_ashr_i32 s13, s13, 6
	s_add_i32 s13, s13, s28
	s_lshl_b32 s28, s13, 3
	s_sub_i32 s29, 0x100, s28
	s_min_i32 s29, s29, 8
	s_mulk_i32 s13, 0xa0
	s_sub_i32 s11, s11, s13
	s_lshr_b32 s56, s11, 3
	s_and_b32 s11, s11, 7
	s_add_i32 s58, s28, s11

;     DI bool next(int i, Unit& u) const {
;     ...
;         int wgid = (int)L; { const int q = nwg / NXCD, r = nwg % NXCD, xcd = wgid % NXCD, off = wgid / NXCD; wgid = (xcd < r ? xcd * (q + 1) : r * (q + 1) + (xcd - r) * q) + off; }
;         const int nig = WGM * nN, gid = wgid / nig, fm = gid * WGM, gsz = (nM - fm) < WGM ? (nM - fm) : WGM;
;         u.pm = fm + ((wgid % nig) % gsz); u.pn = (wgid % nig) / gsz; return true;
.LBB0_970:
	s_ashr_i32 s36, s38, 3
	s_add_i32 s36, s40, s36
	s_ashr_i32 s37, s36, 31
	s_lshr_b32 s37, s37, 27
	s_add_i32 s37, s36, s37
	s_ashr_i32 s38, s37, 5
	s_lshl_b32 s38, s38, 3
	s_sub_i32 s39, 0x100, s38
	s_min_i32 s39, s39, 8
	s_andn2_b32 s37, s37, 31
	s_sub_i32 s37, s36, s37
	s_lshr_b32 s36, s37, 3
	s_and_b32 s37, s37, 7
	s_add_i32 s38, s38, s37

;     DI bool next(int i, Unit& u) const {
;     ...
;         int wgid = (int)L; { const int q = nwg / NXCD, r = nwg % NXCD, xcd = wgid % NXCD, off = wgid / NXCD; wgid = (xcd < r ? xcd * (q + 1) : r * (q + 1) + (xcd - r) * q) + off; }
;         const int nig = WGM * nN, gid = wgid / nig, fm = gid * WGM, gsz = (nM - fm) < WGM ? (nM - fm) : WGM;
;         u.pm = fm + ((wgid % nig) % gsz); u.pn = (wgid % nig) / gsz; return true;
.LBB0_1131:
	s_ashr_i32 s20, s34, 3
	s_add_i32 s20, s36, s20
	s_ashr_i32 s21, s20, 31
	s_lshr_b32 s21, s21, 27
	s_add_i32 s21, s20, s21
	s_ashr_i32 s34, s21, 5
	s_lshl_b32 s34, s34, 3
	s_sub_i32 s35, 0x100, s34
	s_min_i32 s35, s35, 8
	s_andn2_b32 s21, s21, 31
	s_sub_i32 s21, s20, s21
	s_lshr_b32 s20, s21, 3
	s_and_b32 s21, s21, 7
	s_add_i32 s34, s34, s21

;     DI bool next(int i, Unit& u) const {
;     ...
;         int wgid = (int)L; { const int q = nwg / NXCD, r = nwg % NXCD, xcd = wgid % NXCD, off = wgid / NXCD; wgid = (xcd < r ? xcd * (q + 1) : r * (q + 1) + (xcd - r) * q) + off; }
;         const int nig = WGM * nN, gid = wgid / nig, fm = gid * WGM, gsz = (nM - fm) < WGM ? (nM - fm) : WGM;
;         u.pm = fm + ((wgid % nig) % gsz); u.pn = (wgid % nig) / gsz; return true;
.LBB0_1325:
	s_ashr_i32 s0, s14, 3
	s_add_i32 s0, s20, s0
	s_ashr_i32 s1, s0, 31
	s_lshr_b32 s1, s1, 27
	s_add_i32 s1, s0, s1
	s_ashr_i32 s14, s1, 5
	s_lshl_b32 s14, s14, 3
	s_sub_i32 s15, 0x100, s14
	s_min_i32 s15, s15, 8
	s_andn2_b32 s1, s1, 31
	s_sub_i32 s0, s0, s1
	s_lshr_b32 s41, s0, 3
	s_and_b32 s0, s0, 7
	s_add_i32 s42, s14, s0
